# plus P3 mid-K row statistics prefetched at tile start and the gelu in-projection epilogue re-emitted with packed fp32 math (bit-identical)
# speedup vs baseline: 1.0060x; 1.0008x over previous
; __device__ __forceinline__ unsigned pk2(float lo, float hi) { f32x2 v = {lo, hi}; bf16x2_t b = __builtin_convertvector(v, bf16x2_t); return __builtin_bit_cast(unsigned, b); }
; __device__ __forceinline__ float gelu_t(float x) {
;     const float t = x * (1.0f + 0.044715f * x * x) * (-2.0f * 0.7978845608028654f * 1.4426950408889634f);
;     return x * __builtin_amdgcn_rcpf(1.0f + __builtin_amdgcn_exp2f(t));
; }
;     __device__ __forceinline__ void operator()(const f32x4 (&acc)[2][2][4][2], const Unit& u, int wr, int wc, int fr, int fq) const {
;     ...
;             bf16_t* base = (sec == 3 ? U : G);
;             const int col0 = 256 * half + 64 * wc + 8 * fq;
; #pragma unroll
;             for (int ai = 0; ai < 2; ++ai)
; #pragma unroll
;                 for (int m = 0; m < 4; ++m) {
;                     const size_t row = (size_t)u.pm * 256 + 128 * wr + 64 * ai + 16 * m + fr;
; #pragma unroll
;                     for (int bj = 0; bj < 2; ++bj) {
;                         const f32x4 a0 = acc[ai][bj][m][0], a1 = acc[ai][bj][m][1];
;                         u32x4 w; w.x = pk2(gelu_t(a0[0]), gelu_t(a0[1])); w.y = pk2(gelu_t(a0[2]), gelu_t(a0[3]));
;                         w.z = pk2(gelu_t(a1[0]), gelu_t(a1[1])); w.w = pk2(gelu_t(a1[2]), gelu_t(a1[3]));
;                         *(u32x4*)(base + row * 512 + col0 + 32 * bj) = w;
;                     }
;                 }
.LBB0_102:
	s_add_u32 s24, s84, s24
	s_addc_u32 s25, s85, s25
	v_lshl_or_b32 v132, s11, 9, v170
	v_lshl_add_u64 v[142:143], s[24:25], 0, v[132:133]
	s_ashr_i32 s19, s18, 31
	s_lshl_b64 s[24:25], s[18:19], 18
	v_lshl_add_u64 v[142:143], v[142:143], 0, s[24:25]
	v_lshl_add_u64 v[142:143], v[142:143], 0, v[134:135]
	s_mov_b64 s[24:25], 0
	s_mov_b32 s28, 0x3d372713
	s_mov_b32 s29, 0x3d372713
	s_mov_b32 s30, 0xc0135761
	s_mov_b32 s31, 0xc0135761
	v_mov_b32_e32 v188, 1.0
	v_mov_b32_e32 v189, 1.0
	v_pk_mul_f32 v[190:191], v[126:127], s[28:29]
	v_pk_mul_f32 v[192:193], v[128:129], s[28:29]
	v_pk_mul_f32 v[194:195], v[122:123], s[28:29]
	v_pk_mul_f32 v[196:197], v[124:125], s[28:29]
	v_pk_fma_f32 v[190:191], v[126:127], v[190:191], v[188:189]
	v_pk_fma_f32 v[192:193], v[128:129], v[192:193], v[188:189]
	v_pk_fma_f32 v[194:195], v[122:123], v[194:195], v[188:189]
	v_pk_fma_f32 v[196:197], v[124:125], v[196:197], v[188:189]
	v_pk_mul_f32 v[190:191], v[126:127], v[190:191]
	v_pk_mul_f32 v[192:193], v[128:129], v[192:193]
	v_pk_mul_f32 v[194:195], v[122:123], v[194:195]
	v_pk_mul_f32 v[196:197], v[124:125], v[196:197]
	v_pk_mul_f32 v[190:191], v[190:191], s[30:31]
	v_pk_mul_f32 v[192:193], v[192:193], s[30:31]
	v_pk_mul_f32 v[194:195], v[194:195], s[30:31]
	v_pk_mul_f32 v[196:197], v[196:197], s[30:31]
	v_exp_f32_e32 v190, v190
	v_exp_f32_e32 v191, v191
	v_exp_f32_e32 v192, v192
	v_exp_f32_e32 v193, v193
	v_exp_f32_e32 v194, v194
	v_exp_f32_e32 v195, v195
	v_exp_f32_e32 v196, v196
	v_exp_f32_e32 v197, v197
	v_pk_add_f32 v[190:191], v[190:191], v[188:189]
	v_pk_add_f32 v[192:193], v[192:193], v[188:189]
	v_pk_add_f32 v[194:195], v[194:195], v[188:189]
	v_pk_add_f32 v[196:197], v[196:197], v[188:189]
	v_rcp_f32_e32 v190, v190
	v_rcp_f32_e32 v191, v191
	v_rcp_f32_e32 v192, v192
	v_rcp_f32_e32 v193, v193
	v_rcp_f32_e32 v194, v194
	v_rcp_f32_e32 v195, v195
	v_rcp_f32_e32 v196, v196
	v_rcp_f32_e32 v197, v197
	v_pk_mul_f32 v[126:127], v[126:127], v[190:191]
	v_pk_mul_f32 v[128:129], v[128:129], v[192:193]
	v_pk_mul_f32 v[122:123], v[122:123], v[194:195]
	v_pk_mul_f32 v[124:125], v[124:125], v[196:197]
	v_cvt_pk_bf16_f32 v126, v126, v127
	v_cvt_pk_bf16_f32 v127, v128, v129
	v_cvt_pk_bf16_f32 v128, v122, v123
	v_cvt_pk_bf16_f32 v129, v124, v125
	global_store_dwordx4 v[142:143], v[126:129], off
	v_pk_mul_f32 v[190:191], v[118:119], s[28:29]
	v_pk_mul_f32 v[192:193], v[120:121], s[28:29]
	v_pk_mul_f32 v[194:195], v[114:115], s[28:29]
	v_pk_mul_f32 v[196:197], v[116:117], s[28:29]
	v_pk_fma_f32 v[190:191], v[118:119], v[190:191], v[188:189]
	v_pk_fma_f32 v[192:193], v[120:121], v[192:193], v[188:189]
	v_pk_fma_f32 v[194:195], v[114:115], v[194:195], v[188:189]
	v_pk_fma_f32 v[196:197], v[116:117], v[196:197], v[188:189]
	v_pk_mul_f32 v[190:191], v[118:119], v[190:191]
	v_pk_mul_f32 v[192:193], v[120:121], v[192:193]
	v_pk_mul_f32 v[194:195], v[114:115], v[194:195]
	v_pk_mul_f32 v[196:197], v[116:117], v[196:197]
	v_pk_mul_f32 v[190:191], v[190:191], s[30:31]
	v_pk_mul_f32 v[192:193], v[192:193], s[30:31]
	v_pk_mul_f32 v[194:195], v[194:195], s[30:31]
	v_pk_mul_f32 v[196:197], v[196:197], s[30:31]
	v_exp_f32_e32 v190, v190
	v_exp_f32_e32 v191, v191
	v_exp_f32_e32 v192, v192
	v_exp_f32_e32 v193, v193
	v_exp_f32_e32 v194, v194
	v_exp_f32_e32 v195, v195
	v_exp_f32_e32 v196, v196
	v_exp_f32_e32 v197, v197
	v_pk_add_f32 v[190:191], v[190:191], v[188:189]
	v_pk_add_f32 v[192:193], v[192:193], v[188:189]
	v_pk_add_f32 v[194:195], v[194:195], v[188:189]
	v_pk_add_f32 v[196:197], v[196:197], v[188:189]
	v_rcp_f32_e32 v190, v190
	v_rcp_f32_e32 v191, v191
	v_rcp_f32_e32 v192, v192
	v_rcp_f32_e32 v193, v193
	v_rcp_f32_e32 v194, v194
	v_rcp_f32_e32 v195, v195
	v_rcp_f32_e32 v196, v196
	v_rcp_f32_e32 v197, v197
	v_pk_mul_f32 v[118:119], v[118:119], v[190:191]
	v_pk_mul_f32 v[120:121], v[120:121], v[192:193]
	v_pk_mul_f32 v[114:115], v[114:115], v[194:195]
	v_pk_mul_f32 v[116:117], v[116:117], v[196:197]
	v_cvt_pk_bf16_f32 v118, v118, v119
	v_cvt_pk_bf16_f32 v119, v120, v121
	v_cvt_pk_bf16_f32 v120, v114, v115
	v_cvt_pk_bf16_f32 v121, v116, v117
	global_store_dwordx4 v[142:143], v[118:121], off offset:64
	s_mov_b64 s[26:27], 0x4000
	v_lshl_add_u64 v[186:187], v[142:143], 0, s[26:27]
	v_pk_mul_f32 v[190:191], v[110:111], s[28:29]
	v_pk_mul_f32 v[192:193], v[112:113], s[28:29]
	v_pk_mul_f32 v[194:195], v[106:107], s[28:29]
	v_pk_mul_f32 v[196:197], v[108:109], s[28:29]
	v_pk_fma_f32 v[190:191], v[110:111], v[190:191], v[188:189]
	v_pk_fma_f32 v[192:193], v[112:113], v[192:193], v[188:189]
	v_pk_fma_f32 v[194:195], v[106:107], v[194:195], v[188:189]
	v_pk_fma_f32 v[196:197], v[108:109], v[196:197], v[188:189]
	v_pk_mul_f32 v[190:191], v[110:111], v[190:191]
	v_pk_mul_f32 v[192:193], v[112:113], v[192:193]
	v_pk_mul_f32 v[194:195], v[106:107], v[194:195]
	v_pk_mul_f32 v[196:197], v[108:109], v[196:197]
	v_pk_mul_f32 v[190:191], v[190:191], s[30:31]
	v_pk_mul_f32 v[192:193], v[192:193], s[30:31]
	v_pk_mul_f32 v[194:195], v[194:195], s[30:31]
	v_pk_mul_f32 v[196:197], v[196:197], s[30:31]
	v_exp_f32_e32 v190, v190
	v_exp_f32_e32 v191, v191
	v_exp_f32_e32 v192, v192
	v_exp_f32_e32 v193, v193
	v_exp_f32_e32 v194, v194
	v_exp_f32_e32 v195, v195
	v_exp_f32_e32 v196, v196
	v_exp_f32_e32 v197, v197
	v_pk_add_f32 v[190:191], v[190:191], v[188:189]
	v_pk_add_f32 v[192:193], v[192:193], v[188:189]
	v_pk_add_f32 v[194:195], v[194:195], v[188:189]
	v_pk_add_f32 v[196:197], v[196:197], v[188:189]
	v_rcp_f32_e32 v190, v190
	v_rcp_f32_e32 v191, v191
	v_rcp_f32_e32 v192, v192
	v_rcp_f32_e32 v193, v193
	v_rcp_f32_e32 v194, v194
	v_rcp_f32_e32 v195, v195
	v_rcp_f32_e32 v196, v196
	v_rcp_f32_e32 v197, v197
; __device__ __forceinline__ unsigned pk2(float lo, float hi) { f32x2 v = {lo, hi}; bf16x2_t b = __builtin_convertvector(v, bf16x2_t); return __builtin_bit_cast(unsigned, b); }
; __device__ __forceinline__ float gelu_t(float x) {
;     const float t = x * (1.0f + 0.044715f * x * x) * (-2.0f * 0.7978845608028654f * 1.4426950408889634f);
;     return x * __builtin_amdgcn_rcpf(1.0f + __builtin_amdgcn_exp2f(t));
; }
;     __device__ __forceinline__ void operator()(const f32x4 (&acc)[2][2][4][2], const Unit& u, int wr, int wc, int fr, int fq) const {
;     ...
;             for (int ai = 0; ai < 2; ++ai)
; #pragma unroll
;                 for (int m = 0; m < 4; ++m) {
;                     const size_t row = (size_t)u.pm * 256 + 128 * wr + 64 * ai + 16 * m + fr;
; #pragma unroll
;                     for (int bj = 0; bj < 2; ++bj) {
;                         const f32x4 a0 = acc[ai][bj][m][0], a1 = acc[ai][bj][m][1];
;                         u32x4 w; w.x = pk2(gelu_t(a0[0]), gelu_t(a0[1])); w.y = pk2(gelu_t(a0[2]), gelu_t(a0[3]));
;                         w.z = pk2(gelu_t(a1[0]), gelu_t(a1[1])); w.w = pk2(gelu_t(a1[2]), gelu_t(a1[3]));
;                         *(u32x4*)(base + row * 512 + col0 + 32 * bj) = w;
;                     }
;                 }
	v_pk_mul_f32 v[110:111], v[110:111], v[190:191]
	v_pk_mul_f32 v[112:113], v[112:113], v[192:193]
	v_pk_mul_f32 v[106:107], v[106:107], v[194:195]
	v_pk_mul_f32 v[108:109], v[108:109], v[196:197]
	v_cvt_pk_bf16_f32 v110, v110, v111
	v_cvt_pk_bf16_f32 v111, v112, v113
	v_cvt_pk_bf16_f32 v112, v106, v107
	v_cvt_pk_bf16_f32 v113, v108, v109
	global_store_dwordx4 v[186:187], v[110:113], off
	v_pk_mul_f32 v[190:191], v[102:103], s[28:29]
	v_pk_mul_f32 v[192:193], v[104:105], s[28:29]
	v_pk_mul_f32 v[194:195], v[98:99], s[28:29]
	v_pk_mul_f32 v[196:197], v[100:101], s[28:29]
	v_pk_fma_f32 v[190:191], v[102:103], v[190:191], v[188:189]
	v_pk_fma_f32 v[192:193], v[104:105], v[192:193], v[188:189]
	v_pk_fma_f32 v[194:195], v[98:99], v[194:195], v[188:189]
	v_pk_fma_f32 v[196:197], v[100:101], v[196:197], v[188:189]
	v_pk_mul_f32 v[190:191], v[102:103], v[190:191]
	v_pk_mul_f32 v[192:193], v[104:105], v[192:193]
	v_pk_mul_f32 v[194:195], v[98:99], v[194:195]
	v_pk_mul_f32 v[196:197], v[100:101], v[196:197]
	v_pk_mul_f32 v[190:191], v[190:191], s[30:31]
	v_pk_mul_f32 v[192:193], v[192:193], s[30:31]
	v_pk_mul_f32 v[194:195], v[194:195], s[30:31]
	v_pk_mul_f32 v[196:197], v[196:197], s[30:31]
	v_exp_f32_e32 v190, v190
	v_exp_f32_e32 v191, v191
	v_exp_f32_e32 v192, v192
	v_exp_f32_e32 v193, v193
	v_exp_f32_e32 v194, v194
	v_exp_f32_e32 v195, v195
	v_exp_f32_e32 v196, v196
	v_exp_f32_e32 v197, v197
	v_pk_add_f32 v[190:191], v[190:191], v[188:189]
	v_pk_add_f32 v[192:193], v[192:193], v[188:189]
	v_pk_add_f32 v[194:195], v[194:195], v[188:189]
	v_pk_add_f32 v[196:197], v[196:197], v[188:189]
	v_rcp_f32_e32 v190, v190
	v_rcp_f32_e32 v191, v191
	v_rcp_f32_e32 v192, v192
	v_rcp_f32_e32 v193, v193
	v_rcp_f32_e32 v194, v194
	v_rcp_f32_e32 v195, v195
	v_rcp_f32_e32 v196, v196
	v_rcp_f32_e32 v197, v197
	v_pk_mul_f32 v[102:103], v[102:103], v[190:191]
	v_pk_mul_f32 v[104:105], v[104:105], v[192:193]
	v_pk_mul_f32 v[98:99], v[98:99], v[194:195]
	v_pk_mul_f32 v[100:101], v[100:101], v[196:197]
	v_cvt_pk_bf16_f32 v102, v102, v103
	v_cvt_pk_bf16_f32 v103, v104, v105
	v_cvt_pk_bf16_f32 v104, v98, v99
	v_cvt_pk_bf16_f32 v105, v100, v101
	global_store_dwordx4 v[186:187], v[102:105], off offset:64
	s_mov_b64 s[26:27], 0x8000
	v_lshl_add_u64 v[186:187], v[142:143], 0, s[26:27]
	v_pk_mul_f32 v[190:191], v[94:95], s[28:29]
	v_pk_mul_f32 v[192:193], v[96:97], s[28:29]
	v_pk_mul_f32 v[194:195], v[90:91], s[28:29]
	v_pk_mul_f32 v[196:197], v[92:93], s[28:29]
	v_pk_fma_f32 v[190:191], v[94:95], v[190:191], v[188:189]
	v_pk_fma_f32 v[192:193], v[96:97], v[192:193], v[188:189]
	v_pk_fma_f32 v[194:195], v[90:91], v[194:195], v[188:189]
	v_pk_fma_f32 v[196:197], v[92:93], v[196:197], v[188:189]
	v_pk_mul_f32 v[190:191], v[94:95], v[190:191]
	v_pk_mul_f32 v[192:193], v[96:97], v[192:193]
	v_pk_mul_f32 v[194:195], v[90:91], v[194:195]
	v_pk_mul_f32 v[196:197], v[92:93], v[196:197]
	v_pk_mul_f32 v[190:191], v[190:191], s[30:31]
	v_pk_mul_f32 v[192:193], v[192:193], s[30:31]
	v_pk_mul_f32 v[194:195], v[194:195], s[30:31]
	v_pk_mul_f32 v[196:197], v[196:197], s[30:31]
	v_exp_f32_e32 v190, v190
	v_exp_f32_e32 v191, v191
	v_exp_f32_e32 v192, v192
	v_exp_f32_e32 v193, v193
	v_exp_f32_e32 v194, v194
	v_exp_f32_e32 v195, v195
	v_exp_f32_e32 v196, v196
	v_exp_f32_e32 v197, v197
	v_pk_add_f32 v[190:191], v[190:191], v[188:189]
	v_pk_add_f32 v[192:193], v[192:193], v[188:189]
	v_pk_add_f32 v[194:195], v[194:195], v[188:189]
	v_pk_add_f32 v[196:197], v[196:197], v[188:189]
	v_rcp_f32_e32 v190, v190
	v_rcp_f32_e32 v191, v191
	v_rcp_f32_e32 v192, v192
	v_rcp_f32_e32 v193, v193
	v_rcp_f32_e32 v194, v194
	v_rcp_f32_e32 v195, v195
	v_rcp_f32_e32 v196, v196
	v_rcp_f32_e32 v197, v197
	v_pk_mul_f32 v[94:95], v[94:95], v[190:191]
	v_pk_mul_f32 v[96:97], v[96:97], v[192:193]
	v_pk_mul_f32 v[90:91], v[90:91], v[194:195]
	v_pk_mul_f32 v[92:93], v[92:93], v[196:197]
	v_cvt_pk_bf16_f32 v94, v94, v95
	v_cvt_pk_bf16_f32 v95, v96, v97
	v_cvt_pk_bf16_f32 v96, v90, v91
	v_cvt_pk_bf16_f32 v97, v92, v93
	global_store_dwordx4 v[186:187], v[94:97], off
	v_pk_mul_f32 v[190:191], v[86:87], s[28:29]
	v_pk_mul_f32 v[192:193], v[88:89], s[28:29]
	v_pk_mul_f32 v[194:195], v[82:83], s[28:29]
	v_pk_mul_f32 v[196:197], v[84:85], s[28:29]
	v_pk_fma_f32 v[190:191], v[86:87], v[190:191], v[188:189]
	v_pk_fma_f32 v[192:193], v[88:89], v[192:193], v[188:189]
	v_pk_fma_f32 v[194:195], v[82:83], v[194:195], v[188:189]
	v_pk_fma_f32 v[196:197], v[84:85], v[196:197], v[188:189]
	v_pk_mul_f32 v[190:191], v[86:87], v[190:191]
	v_pk_mul_f32 v[192:193], v[88:89], v[192:193]
	v_pk_mul_f32 v[194:195], v[82:83], v[194:195]
	v_pk_mul_f32 v[196:197], v[84:85], v[196:197]
	v_pk_mul_f32 v[190:191], v[190:191], s[30:31]
	v_pk_mul_f32 v[192:193], v[192:193], s[30:31]
	v_pk_mul_f32 v[194:195], v[194:195], s[30:31]
	v_pk_mul_f32 v[196:197], v[196:197], s[30:31]
	v_exp_f32_e32 v190, v190
	v_exp_f32_e32 v191, v191
	v_exp_f32_e32 v192, v192
	v_exp_f32_e32 v193, v193
	v_exp_f32_e32 v194, v194
	v_exp_f32_e32 v195, v195
	v_exp_f32_e32 v196, v196
	v_exp_f32_e32 v197, v197
	v_pk_add_f32 v[190:191], v[190:191], v[188:189]
	v_pk_add_f32 v[192:193], v[192:193], v[188:189]
	v_pk_add_f32 v[194:195], v[194:195], v[188:189]
	v_pk_add_f32 v[196:197], v[196:197], v[188:189]
	v_rcp_f32_e32 v190, v190
	v_rcp_f32_e32 v191, v191
	v_rcp_f32_e32 v192, v192
	v_rcp_f32_e32 v193, v193
	v_rcp_f32_e32 v194, v194
	v_rcp_f32_e32 v195, v195
	v_rcp_f32_e32 v196, v196
	v_rcp_f32_e32 v197, v197
	v_pk_mul_f32 v[86:87], v[86:87], v[190:191]
	v_pk_mul_f32 v[88:89], v[88:89], v[192:193]
	v_pk_mul_f32 v[82:83], v[82:83], v[194:195]
	v_pk_mul_f32 v[84:85], v[84:85], v[196:197]
; __device__ __forceinline__ unsigned pk2(float lo, float hi) { f32x2 v = {lo, hi}; bf16x2_t b = __builtin_convertvector(v, bf16x2_t); return __builtin_bit_cast(unsigned, b); }
; __device__ __forceinline__ float gelu_t(float x) {
;     const float t = x * (1.0f + 0.044715f * x * x) * (-2.0f * 0.7978845608028654f * 1.4426950408889634f);
;     return x * __builtin_amdgcn_rcpf(1.0f + __builtin_amdgcn_exp2f(t));
; }
;     __device__ __forceinline__ void operator()(const f32x4 (&acc)[2][2][4][2], const Unit& u, int wr, int wc, int fr, int fq) const {
;     ...
;             for (int ai = 0; ai < 2; ++ai)
; #pragma unroll
;                 for (int m = 0; m < 4; ++m) {
;                     const size_t row = (size_t)u.pm * 256 + 128 * wr + 64 * ai + 16 * m + fr;
; #pragma unroll
;                     for (int bj = 0; bj < 2; ++bj) {
;                         const f32x4 a0 = acc[ai][bj][m][0], a1 = acc[ai][bj][m][1];
;                         u32x4 w; w.x = pk2(gelu_t(a0[0]), gelu_t(a0[1])); w.y = pk2(gelu_t(a0[2]), gelu_t(a0[3]));
;                         w.z = pk2(gelu_t(a1[0]), gelu_t(a1[1])); w.w = pk2(gelu_t(a1[2]), gelu_t(a1[3]));
;                         *(u32x4*)(base + row * 512 + col0 + 32 * bj) = w;
;                     }
;                 }
	v_cvt_pk_bf16_f32 v86, v86, v87
	v_cvt_pk_bf16_f32 v87, v88, v89
	v_cvt_pk_bf16_f32 v88, v82, v83
	v_cvt_pk_bf16_f32 v89, v84, v85
	global_store_dwordx4 v[186:187], v[86:89], off offset:64
	s_mov_b64 s[26:27], 0xc000
	v_lshl_add_u64 v[186:187], v[142:143], 0, s[26:27]
	v_pk_mul_f32 v[190:191], v[78:79], s[28:29]
	v_pk_mul_f32 v[192:193], v[80:81], s[28:29]
	v_pk_mul_f32 v[194:195], v[74:75], s[28:29]
	v_pk_mul_f32 v[196:197], v[76:77], s[28:29]
	v_pk_fma_f32 v[190:191], v[78:79], v[190:191], v[188:189]
	v_pk_fma_f32 v[192:193], v[80:81], v[192:193], v[188:189]
	v_pk_fma_f32 v[194:195], v[74:75], v[194:195], v[188:189]
	v_pk_fma_f32 v[196:197], v[76:77], v[196:197], v[188:189]
	v_pk_mul_f32 v[190:191], v[78:79], v[190:191]
	v_pk_mul_f32 v[192:193], v[80:81], v[192:193]
	v_pk_mul_f32 v[194:195], v[74:75], v[194:195]
	v_pk_mul_f32 v[196:197], v[76:77], v[196:197]
	v_pk_mul_f32 v[190:191], v[190:191], s[30:31]
	v_pk_mul_f32 v[192:193], v[192:193], s[30:31]
	v_pk_mul_f32 v[194:195], v[194:195], s[30:31]
	v_pk_mul_f32 v[196:197], v[196:197], s[30:31]
	v_exp_f32_e32 v190, v190
	v_exp_f32_e32 v191, v191
	v_exp_f32_e32 v192, v192
	v_exp_f32_e32 v193, v193
	v_exp_f32_e32 v194, v194
	v_exp_f32_e32 v195, v195
	v_exp_f32_e32 v196, v196
	v_exp_f32_e32 v197, v197
	v_pk_add_f32 v[190:191], v[190:191], v[188:189]
	v_pk_add_f32 v[192:193], v[192:193], v[188:189]
	v_pk_add_f32 v[194:195], v[194:195], v[188:189]
	v_pk_add_f32 v[196:197], v[196:197], v[188:189]
	v_rcp_f32_e32 v190, v190
	v_rcp_f32_e32 v191, v191
	v_rcp_f32_e32 v192, v192
	v_rcp_f32_e32 v193, v193
	v_rcp_f32_e32 v194, v194
	v_rcp_f32_e32 v195, v195
	v_rcp_f32_e32 v196, v196
	v_rcp_f32_e32 v197, v197
	v_pk_mul_f32 v[78:79], v[78:79], v[190:191]
	v_pk_mul_f32 v[80:81], v[80:81], v[192:193]
	v_pk_mul_f32 v[74:75], v[74:75], v[194:195]
	v_pk_mul_f32 v[76:77], v[76:77], v[196:197]
	v_cvt_pk_bf16_f32 v78, v78, v79
	v_cvt_pk_bf16_f32 v79, v80, v81
	v_cvt_pk_bf16_f32 v80, v74, v75
	v_cvt_pk_bf16_f32 v81, v76, v77
	global_store_dwordx4 v[186:187], v[78:81], off
	v_pk_mul_f32 v[190:191], v[70:71], s[28:29]
	v_pk_mul_f32 v[192:193], v[72:73], s[28:29]
	v_pk_mul_f32 v[194:195], v[66:67], s[28:29]
	v_pk_mul_f32 v[196:197], v[68:69], s[28:29]
	v_pk_fma_f32 v[190:191], v[70:71], v[190:191], v[188:189]
	v_pk_fma_f32 v[192:193], v[72:73], v[192:193], v[188:189]
	v_pk_fma_f32 v[194:195], v[66:67], v[194:195], v[188:189]
	v_pk_fma_f32 v[196:197], v[68:69], v[196:197], v[188:189]
	v_pk_mul_f32 v[190:191], v[70:71], v[190:191]
	v_pk_mul_f32 v[192:193], v[72:73], v[192:193]
	v_pk_mul_f32 v[194:195], v[66:67], v[194:195]
	v_pk_mul_f32 v[196:197], v[68:69], v[196:197]
	v_pk_mul_f32 v[190:191], v[190:191], s[30:31]
	v_pk_mul_f32 v[192:193], v[192:193], s[30:31]
	v_pk_mul_f32 v[194:195], v[194:195], s[30:31]
	v_pk_mul_f32 v[196:197], v[196:197], s[30:31]
	v_exp_f32_e32 v190, v190
	v_exp_f32_e32 v191, v191
	v_exp_f32_e32 v192, v192
	v_exp_f32_e32 v193, v193
	v_exp_f32_e32 v194, v194
	v_exp_f32_e32 v195, v195
	v_exp_f32_e32 v196, v196
	v_exp_f32_e32 v197, v197
	v_pk_add_f32 v[190:191], v[190:191], v[188:189]
	v_pk_add_f32 v[192:193], v[192:193], v[188:189]
	v_pk_add_f32 v[194:195], v[194:195], v[188:189]
	v_pk_add_f32 v[196:197], v[196:197], v[188:189]
	v_rcp_f32_e32 v190, v190
	v_rcp_f32_e32 v191, v191
	v_rcp_f32_e32 v192, v192
	v_rcp_f32_e32 v193, v193
	v_rcp_f32_e32 v194, v194
	v_rcp_f32_e32 v195, v195
	v_rcp_f32_e32 v196, v196
	v_rcp_f32_e32 v197, v197
	v_pk_mul_f32 v[70:71], v[70:71], v[190:191]
	v_pk_mul_f32 v[72:73], v[72:73], v[192:193]
	v_pk_mul_f32 v[66:67], v[66:67], v[194:195]
	v_pk_mul_f32 v[68:69], v[68:69], v[196:197]
	v_cvt_pk_bf16_f32 v70, v70, v71
	v_cvt_pk_bf16_f32 v71, v72, v73
	v_cvt_pk_bf16_f32 v72, v66, v67
	v_cvt_pk_bf16_f32 v73, v68, v69
	global_store_dwordx4 v[186:187], v[70:73], off offset:64
	s_mov_b64 s[26:27], 0x10000
	v_lshl_add_u64 v[186:187], v[142:143], 0, s[26:27]
	v_pk_mul_f32 v[190:191], v[62:63], s[28:29]
	v_pk_mul_f32 v[192:193], v[64:65], s[28:29]
	v_pk_mul_f32 v[194:195], v[58:59], s[28:29]
	v_pk_mul_f32 v[196:197], v[60:61], s[28:29]
	v_pk_fma_f32 v[190:191], v[62:63], v[190:191], v[188:189]
	v_pk_fma_f32 v[192:193], v[64:65], v[192:193], v[188:189]
	v_pk_fma_f32 v[194:195], v[58:59], v[194:195], v[188:189]
	v_pk_fma_f32 v[196:197], v[60:61], v[196:197], v[188:189]
	v_pk_mul_f32 v[190:191], v[62:63], v[190:191]
	v_pk_mul_f32 v[192:193], v[64:65], v[192:193]
	v_pk_mul_f32 v[194:195], v[58:59], v[194:195]
	v_pk_mul_f32 v[196:197], v[60:61], v[196:197]
	v_pk_mul_f32 v[190:191], v[190:191], s[30:31]
	v_pk_mul_f32 v[192:193], v[192:193], s[30:31]
	v_pk_mul_f32 v[194:195], v[194:195], s[30:31]
	v_pk_mul_f32 v[196:197], v[196:197], s[30:31]
	v_exp_f32_e32 v190, v190
	v_exp_f32_e32 v191, v191
	v_exp_f32_e32 v192, v192
	v_exp_f32_e32 v193, v193
	v_exp_f32_e32 v194, v194
	v_exp_f32_e32 v195, v195
	v_exp_f32_e32 v196, v196
	v_exp_f32_e32 v197, v197
	v_pk_add_f32 v[190:191], v[190:191], v[188:189]
	v_pk_add_f32 v[192:193], v[192:193], v[188:189]
	v_pk_add_f32 v[194:195], v[194:195], v[188:189]
	v_pk_add_f32 v[196:197], v[196:197], v[188:189]
	v_rcp_f32_e32 v190, v190
	v_rcp_f32_e32 v191, v191
	v_rcp_f32_e32 v192, v192
	v_rcp_f32_e32 v193, v193
	v_rcp_f32_e32 v194, v194
	v_rcp_f32_e32 v195, v195
	v_rcp_f32_e32 v196, v196
	v_rcp_f32_e32 v197, v197
	v_pk_mul_f32 v[62:63], v[62:63], v[190:191]
	v_pk_mul_f32 v[64:65], v[64:65], v[192:193]
	v_pk_mul_f32 v[58:59], v[58:59], v[194:195]
	v_pk_mul_f32 v[60:61], v[60:61], v[196:197]
	v_cvt_pk_bf16_f32 v62, v62, v63
	v_cvt_pk_bf16_f32 v63, v64, v65
	v_cvt_pk_bf16_f32 v64, v58, v59
	v_cvt_pk_bf16_f32 v65, v60, v61
	global_store_dwordx4 v[186:187], v[62:65], off
; __device__ __forceinline__ unsigned pk2(float lo, float hi) { f32x2 v = {lo, hi}; bf16x2_t b = __builtin_convertvector(v, bf16x2_t); return __builtin_bit_cast(unsigned, b); }
; __device__ __forceinline__ float gelu_t(float x) {
;     const float t = x * (1.0f + 0.044715f * x * x) * (-2.0f * 0.7978845608028654f * 1.4426950408889634f);
;     return x * __builtin_amdgcn_rcpf(1.0f + __builtin_amdgcn_exp2f(t));
; }
;     __device__ __forceinline__ void operator()(const f32x4 (&acc)[2][2][4][2], const Unit& u, int wr, int wc, int fr, int fq) const {
;     ...
;             for (int ai = 0; ai < 2; ++ai)
; #pragma unroll
;                 for (int m = 0; m < 4; ++m) {
;                     const size_t row = (size_t)u.pm * 256 + 128 * wr + 64 * ai + 16 * m + fr;
; #pragma unroll
;                     for (int bj = 0; bj < 2; ++bj) {
;                         const f32x4 a0 = acc[ai][bj][m][0], a1 = acc[ai][bj][m][1];
;                         u32x4 w; w.x = pk2(gelu_t(a0[0]), gelu_t(a0[1])); w.y = pk2(gelu_t(a0[2]), gelu_t(a0[3]));
;                         w.z = pk2(gelu_t(a1[0]), gelu_t(a1[1])); w.w = pk2(gelu_t(a1[2]), gelu_t(a1[3]));
;                         *(u32x4*)(base + row * 512 + col0 + 32 * bj) = w;
;                     }
;                 }
	v_pk_mul_f32 v[190:191], v[54:55], s[28:29]
	v_pk_mul_f32 v[192:193], v[56:57], s[28:29]
	v_pk_mul_f32 v[194:195], v[50:51], s[28:29]
	v_pk_mul_f32 v[196:197], v[52:53], s[28:29]
	v_pk_fma_f32 v[190:191], v[54:55], v[190:191], v[188:189]
	v_pk_fma_f32 v[192:193], v[56:57], v[192:193], v[188:189]
	v_pk_fma_f32 v[194:195], v[50:51], v[194:195], v[188:189]
	v_pk_fma_f32 v[196:197], v[52:53], v[196:197], v[188:189]
	v_pk_mul_f32 v[190:191], v[54:55], v[190:191]
	v_pk_mul_f32 v[192:193], v[56:57], v[192:193]
	v_pk_mul_f32 v[194:195], v[50:51], v[194:195]
	v_pk_mul_f32 v[196:197], v[52:53], v[196:197]
	v_pk_mul_f32 v[190:191], v[190:191], s[30:31]
	v_pk_mul_f32 v[192:193], v[192:193], s[30:31]
	v_pk_mul_f32 v[194:195], v[194:195], s[30:31]
	v_pk_mul_f32 v[196:197], v[196:197], s[30:31]
	v_exp_f32_e32 v190, v190
	v_exp_f32_e32 v191, v191
	v_exp_f32_e32 v192, v192
	v_exp_f32_e32 v193, v193
	v_exp_f32_e32 v194, v194
	v_exp_f32_e32 v195, v195
	v_exp_f32_e32 v196, v196
	v_exp_f32_e32 v197, v197
	v_pk_add_f32 v[190:191], v[190:191], v[188:189]
	v_pk_add_f32 v[192:193], v[192:193], v[188:189]
	v_pk_add_f32 v[194:195], v[194:195], v[188:189]
	v_pk_add_f32 v[196:197], v[196:197], v[188:189]
	v_rcp_f32_e32 v190, v190
	v_rcp_f32_e32 v191, v191
	v_rcp_f32_e32 v192, v192
	v_rcp_f32_e32 v193, v193
	v_rcp_f32_e32 v194, v194
	v_rcp_f32_e32 v195, v195
	v_rcp_f32_e32 v196, v196
	v_rcp_f32_e32 v197, v197
	v_pk_mul_f32 v[54:55], v[54:55], v[190:191]
	v_pk_mul_f32 v[56:57], v[56:57], v[192:193]
	v_pk_mul_f32 v[50:51], v[50:51], v[194:195]
	v_pk_mul_f32 v[52:53], v[52:53], v[196:197]
	v_cvt_pk_bf16_f32 v54, v54, v55
	v_cvt_pk_bf16_f32 v55, v56, v57
	v_cvt_pk_bf16_f32 v56, v50, v51
	v_cvt_pk_bf16_f32 v57, v52, v53
	global_store_dwordx4 v[186:187], v[54:57], off offset:64
	s_mov_b64 s[26:27], 0x14000
	v_lshl_add_u64 v[186:187], v[142:143], 0, s[26:27]
	v_pk_mul_f32 v[190:191], v[46:47], s[28:29]
	v_pk_mul_f32 v[192:193], v[48:49], s[28:29]
	v_pk_mul_f32 v[194:195], v[42:43], s[28:29]
	v_pk_mul_f32 v[196:197], v[44:45], s[28:29]
	v_pk_fma_f32 v[190:191], v[46:47], v[190:191], v[188:189]
	v_pk_fma_f32 v[192:193], v[48:49], v[192:193], v[188:189]
	v_pk_fma_f32 v[194:195], v[42:43], v[194:195], v[188:189]
	v_pk_fma_f32 v[196:197], v[44:45], v[196:197], v[188:189]
	v_pk_mul_f32 v[190:191], v[46:47], v[190:191]
	v_pk_mul_f32 v[192:193], v[48:49], v[192:193]
	v_pk_mul_f32 v[194:195], v[42:43], v[194:195]
	v_pk_mul_f32 v[196:197], v[44:45], v[196:197]
	v_pk_mul_f32 v[190:191], v[190:191], s[30:31]
	v_pk_mul_f32 v[192:193], v[192:193], s[30:31]
	v_pk_mul_f32 v[194:195], v[194:195], s[30:31]
	v_pk_mul_f32 v[196:197], v[196:197], s[30:31]
	v_exp_f32_e32 v190, v190
	v_exp_f32_e32 v191, v191
	v_exp_f32_e32 v192, v192
	v_exp_f32_e32 v193, v193
	v_exp_f32_e32 v194, v194
	v_exp_f32_e32 v195, v195
	v_exp_f32_e32 v196, v196
	v_exp_f32_e32 v197, v197
	v_pk_add_f32 v[190:191], v[190:191], v[188:189]
	v_pk_add_f32 v[192:193], v[192:193], v[188:189]
	v_pk_add_f32 v[194:195], v[194:195], v[188:189]
	v_pk_add_f32 v[196:197], v[196:197], v[188:189]
	v_rcp_f32_e32 v190, v190
	v_rcp_f32_e32 v191, v191
	v_rcp_f32_e32 v192, v192
	v_rcp_f32_e32 v193, v193
	v_rcp_f32_e32 v194, v194
	v_rcp_f32_e32 v195, v195
	v_rcp_f32_e32 v196, v196
	v_rcp_f32_e32 v197, v197
	v_pk_mul_f32 v[46:47], v[46:47], v[190:191]
	v_pk_mul_f32 v[48:49], v[48:49], v[192:193]
	v_pk_mul_f32 v[42:43], v[42:43], v[194:195]
	v_pk_mul_f32 v[44:45], v[44:45], v[196:197]
	v_cvt_pk_bf16_f32 v46, v46, v47
	v_cvt_pk_bf16_f32 v47, v48, v49
	v_cvt_pk_bf16_f32 v48, v42, v43
	v_cvt_pk_bf16_f32 v49, v44, v45
	global_store_dwordx4 v[186:187], v[46:49], off
	v_pk_mul_f32 v[190:191], v[38:39], s[28:29]
	v_pk_mul_f32 v[192:193], v[40:41], s[28:29]
	v_pk_mul_f32 v[194:195], v[34:35], s[28:29]
	v_pk_mul_f32 v[196:197], v[36:37], s[28:29]
	v_pk_fma_f32 v[190:191], v[38:39], v[190:191], v[188:189]
	v_pk_fma_f32 v[192:193], v[40:41], v[192:193], v[188:189]
	v_pk_fma_f32 v[194:195], v[34:35], v[194:195], v[188:189]
	v_pk_fma_f32 v[196:197], v[36:37], v[196:197], v[188:189]
	v_pk_mul_f32 v[190:191], v[38:39], v[190:191]
	v_pk_mul_f32 v[192:193], v[40:41], v[192:193]
	v_pk_mul_f32 v[194:195], v[34:35], v[194:195]
	v_pk_mul_f32 v[196:197], v[36:37], v[196:197]
	v_pk_mul_f32 v[190:191], v[190:191], s[30:31]
	v_pk_mul_f32 v[192:193], v[192:193], s[30:31]
	v_pk_mul_f32 v[194:195], v[194:195], s[30:31]
	v_pk_mul_f32 v[196:197], v[196:197], s[30:31]
	v_exp_f32_e32 v190, v190
	v_exp_f32_e32 v191, v191
	v_exp_f32_e32 v192, v192
	v_exp_f32_e32 v193, v193
	v_exp_f32_e32 v194, v194
	v_exp_f32_e32 v195, v195
	v_exp_f32_e32 v196, v196
	v_exp_f32_e32 v197, v197
	v_pk_add_f32 v[190:191], v[190:191], v[188:189]
	v_pk_add_f32 v[192:193], v[192:193], v[188:189]
	v_pk_add_f32 v[194:195], v[194:195], v[188:189]
	v_pk_add_f32 v[196:197], v[196:197], v[188:189]
	v_rcp_f32_e32 v190, v190
	v_rcp_f32_e32 v191, v191
	v_rcp_f32_e32 v192, v192
	v_rcp_f32_e32 v193, v193
	v_rcp_f32_e32 v194, v194
	v_rcp_f32_e32 v195, v195
	v_rcp_f32_e32 v196, v196
	v_rcp_f32_e32 v197, v197
	v_pk_mul_f32 v[38:39], v[38:39], v[190:191]
	v_pk_mul_f32 v[40:41], v[40:41], v[192:193]
	v_pk_mul_f32 v[34:35], v[34:35], v[194:195]
	v_pk_mul_f32 v[36:37], v[36:37], v[196:197]
	v_cvt_pk_bf16_f32 v38, v38, v39
	v_cvt_pk_bf16_f32 v39, v40, v41
	v_cvt_pk_bf16_f32 v40, v34, v35
	v_cvt_pk_bf16_f32 v41, v36, v37
	global_store_dwordx4 v[186:187], v[38:41], off offset:64
	s_mov_b64 s[26:27], 0x18000
	v_lshl_add_u64 v[186:187], v[142:143], 0, s[26:27]
	v_pk_mul_f32 v[190:191], v[30:31], s[28:29]
	v_pk_mul_f32 v[192:193], v[32:33], s[28:29]
	v_pk_mul_f32 v[194:195], v[26:27], s[28:29]
	v_pk_mul_f32 v[196:197], v[28:29], s[28:29]
; __device__ __forceinline__ unsigned pk2(float lo, float hi) { f32x2 v = {lo, hi}; bf16x2_t b = __builtin_convertvector(v, bf16x2_t); return __builtin_bit_cast(unsigned, b); }
; __device__ __forceinline__ float gelu_t(float x) {
;     const float t = x * (1.0f + 0.044715f * x * x) * (-2.0f * 0.7978845608028654f * 1.4426950408889634f);
;     return x * __builtin_amdgcn_rcpf(1.0f + __builtin_amdgcn_exp2f(t));
; }
;     __device__ __forceinline__ void operator()(const f32x4 (&acc)[2][2][4][2], const Unit& u, int wr, int wc, int fr, int fq) const {
;     ...
;             for (int ai = 0; ai < 2; ++ai)
; #pragma unroll
;                 for (int m = 0; m < 4; ++m) {
;                     const size_t row = (size_t)u.pm * 256 + 128 * wr + 64 * ai + 16 * m + fr;
; #pragma unroll
;                     for (int bj = 0; bj < 2; ++bj) {
;                         const f32x4 a0 = acc[ai][bj][m][0], a1 = acc[ai][bj][m][1];
;                         u32x4 w; w.x = pk2(gelu_t(a0[0]), gelu_t(a0[1])); w.y = pk2(gelu_t(a0[2]), gelu_t(a0[3]));
;                         w.z = pk2(gelu_t(a1[0]), gelu_t(a1[1])); w.w = pk2(gelu_t(a1[2]), gelu_t(a1[3]));
;                         *(u32x4*)(base + row * 512 + col0 + 32 * bj) = w;
;                     }
;                 }
	v_pk_fma_f32 v[190:191], v[30:31], v[190:191], v[188:189]
	v_pk_fma_f32 v[192:193], v[32:33], v[192:193], v[188:189]
	v_pk_fma_f32 v[194:195], v[26:27], v[194:195], v[188:189]
	v_pk_fma_f32 v[196:197], v[28:29], v[196:197], v[188:189]
	v_pk_mul_f32 v[190:191], v[30:31], v[190:191]
	v_pk_mul_f32 v[192:193], v[32:33], v[192:193]
	v_pk_mul_f32 v[194:195], v[26:27], v[194:195]
	v_pk_mul_f32 v[196:197], v[28:29], v[196:197]
	v_pk_mul_f32 v[190:191], v[190:191], s[30:31]
	v_pk_mul_f32 v[192:193], v[192:193], s[30:31]
	v_pk_mul_f32 v[194:195], v[194:195], s[30:31]
	v_pk_mul_f32 v[196:197], v[196:197], s[30:31]
	v_exp_f32_e32 v190, v190
	v_exp_f32_e32 v191, v191
	v_exp_f32_e32 v192, v192
	v_exp_f32_e32 v193, v193
	v_exp_f32_e32 v194, v194
	v_exp_f32_e32 v195, v195
	v_exp_f32_e32 v196, v196
	v_exp_f32_e32 v197, v197
	v_pk_add_f32 v[190:191], v[190:191], v[188:189]
	v_pk_add_f32 v[192:193], v[192:193], v[188:189]
	v_pk_add_f32 v[194:195], v[194:195], v[188:189]
	v_pk_add_f32 v[196:197], v[196:197], v[188:189]
	v_rcp_f32_e32 v190, v190
	v_rcp_f32_e32 v191, v191
	v_rcp_f32_e32 v192, v192
	v_rcp_f32_e32 v193, v193
	v_rcp_f32_e32 v194, v194
	v_rcp_f32_e32 v195, v195
	v_rcp_f32_e32 v196, v196
	v_rcp_f32_e32 v197, v197
	v_pk_mul_f32 v[30:31], v[30:31], v[190:191]
	v_pk_mul_f32 v[32:33], v[32:33], v[192:193]
	v_pk_mul_f32 v[26:27], v[26:27], v[194:195]
	v_pk_mul_f32 v[28:29], v[28:29], v[196:197]
	v_cvt_pk_bf16_f32 v30, v30, v31
	v_cvt_pk_bf16_f32 v31, v32, v33
	v_cvt_pk_bf16_f32 v32, v26, v27
	v_cvt_pk_bf16_f32 v33, v28, v29
	global_store_dwordx4 v[186:187], v[30:33], off
	v_pk_mul_f32 v[190:191], v[22:23], s[28:29]
	v_pk_mul_f32 v[192:193], v[24:25], s[28:29]
	v_pk_mul_f32 v[194:195], v[18:19], s[28:29]
	v_pk_mul_f32 v[196:197], v[20:21], s[28:29]
	v_pk_fma_f32 v[190:191], v[22:23], v[190:191], v[188:189]
	v_pk_fma_f32 v[192:193], v[24:25], v[192:193], v[188:189]
	v_pk_fma_f32 v[194:195], v[18:19], v[194:195], v[188:189]
	v_pk_fma_f32 v[196:197], v[20:21], v[196:197], v[188:189]
	v_pk_mul_f32 v[190:191], v[22:23], v[190:191]
	v_pk_mul_f32 v[192:193], v[24:25], v[192:193]
	v_pk_mul_f32 v[194:195], v[18:19], v[194:195]
	v_pk_mul_f32 v[196:197], v[20:21], v[196:197]
	v_pk_mul_f32 v[190:191], v[190:191], s[30:31]
	v_pk_mul_f32 v[192:193], v[192:193], s[30:31]
	v_pk_mul_f32 v[194:195], v[194:195], s[30:31]
	v_pk_mul_f32 v[196:197], v[196:197], s[30:31]
	v_exp_f32_e32 v190, v190
	v_exp_f32_e32 v191, v191
	v_exp_f32_e32 v192, v192
	v_exp_f32_e32 v193, v193
	v_exp_f32_e32 v194, v194
	v_exp_f32_e32 v195, v195
	v_exp_f32_e32 v196, v196
	v_exp_f32_e32 v197, v197
	v_pk_add_f32 v[190:191], v[190:191], v[188:189]
	v_pk_add_f32 v[192:193], v[192:193], v[188:189]
	v_pk_add_f32 v[194:195], v[194:195], v[188:189]
	v_pk_add_f32 v[196:197], v[196:197], v[188:189]
	v_rcp_f32_e32 v190, v190
	v_rcp_f32_e32 v191, v191
	v_rcp_f32_e32 v192, v192
	v_rcp_f32_e32 v193, v193
	v_rcp_f32_e32 v194, v194
	v_rcp_f32_e32 v195, v195
	v_rcp_f32_e32 v196, v196
	v_rcp_f32_e32 v197, v197
	v_pk_mul_f32 v[22:23], v[22:23], v[190:191]
	v_pk_mul_f32 v[24:25], v[24:25], v[192:193]
	v_pk_mul_f32 v[18:19], v[18:19], v[194:195]
	v_pk_mul_f32 v[20:21], v[20:21], v[196:197]
	v_cvt_pk_bf16_f32 v22, v22, v23
	v_cvt_pk_bf16_f32 v23, v24, v25
	v_cvt_pk_bf16_f32 v24, v18, v19
	v_cvt_pk_bf16_f32 v25, v20, v21
	global_store_dwordx4 v[186:187], v[22:25], off offset:64
	s_mov_b64 s[26:27], 0x1c000
	v_lshl_add_u64 v[186:187], v[142:143], 0, s[26:27]
	v_pk_mul_f32 v[190:191], v[14:15], s[28:29]
	v_pk_mul_f32 v[192:193], v[16:17], s[28:29]
	v_pk_mul_f32 v[194:195], v[10:11], s[28:29]
	v_pk_mul_f32 v[196:197], v[12:13], s[28:29]
	v_pk_fma_f32 v[190:191], v[14:15], v[190:191], v[188:189]
	v_pk_fma_f32 v[192:193], v[16:17], v[192:193], v[188:189]
	v_pk_fma_f32 v[194:195], v[10:11], v[194:195], v[188:189]
	v_pk_fma_f32 v[196:197], v[12:13], v[196:197], v[188:189]
	v_pk_mul_f32 v[190:191], v[14:15], v[190:191]
	v_pk_mul_f32 v[192:193], v[16:17], v[192:193]
	v_pk_mul_f32 v[194:195], v[10:11], v[194:195]
	v_pk_mul_f32 v[196:197], v[12:13], v[196:197]
	v_pk_mul_f32 v[190:191], v[190:191], s[30:31]
	v_pk_mul_f32 v[192:193], v[192:193], s[30:31]
	v_pk_mul_f32 v[194:195], v[194:195], s[30:31]
	v_pk_mul_f32 v[196:197], v[196:197], s[30:31]
	v_exp_f32_e32 v190, v190
	v_exp_f32_e32 v191, v191
	v_exp_f32_e32 v192, v192
	v_exp_f32_e32 v193, v193
	v_exp_f32_e32 v194, v194
	v_exp_f32_e32 v195, v195
	v_exp_f32_e32 v196, v196
	v_exp_f32_e32 v197, v197
	v_pk_add_f32 v[190:191], v[190:191], v[188:189]
	v_pk_add_f32 v[192:193], v[192:193], v[188:189]
	v_pk_add_f32 v[194:195], v[194:195], v[188:189]
	v_pk_add_f32 v[196:197], v[196:197], v[188:189]
	v_rcp_f32_e32 v190, v190
	v_rcp_f32_e32 v191, v191
	v_rcp_f32_e32 v192, v192
	v_rcp_f32_e32 v193, v193
	v_rcp_f32_e32 v194, v194
	v_rcp_f32_e32 v195, v195
	v_rcp_f32_e32 v196, v196
	v_rcp_f32_e32 v197, v197
	v_pk_mul_f32 v[14:15], v[14:15], v[190:191]
	v_pk_mul_f32 v[16:17], v[16:17], v[192:193]
	v_pk_mul_f32 v[10:11], v[10:11], v[194:195]
	v_pk_mul_f32 v[12:13], v[12:13], v[196:197]
	v_cvt_pk_bf16_f32 v14, v14, v15
	v_cvt_pk_bf16_f32 v15, v16, v17
	v_cvt_pk_bf16_f32 v16, v10, v11
	v_cvt_pk_bf16_f32 v17, v12, v13
	global_store_dwordx4 v[186:187], v[14:17], off
	v_pk_mul_f32 v[190:191], v[6:7], s[28:29]
	v_pk_mul_f32 v[192:193], v[8:9], s[28:29]
	v_pk_mul_f32 v[194:195], v[2:3], s[28:29]
	v_pk_mul_f32 v[196:197], v[4:5], s[28:29]
	v_pk_fma_f32 v[190:191], v[6:7], v[190:191], v[188:189]
	v_pk_fma_f32 v[192:193], v[8:9], v[192:193], v[188:189]
	v_pk_fma_f32 v[194:195], v[2:3], v[194:195], v[188:189]
	v_pk_fma_f32 v[196:197], v[4:5], v[196:197], v[188:189]
	v_pk_mul_f32 v[190:191], v[6:7], v[190:191]
	v_pk_mul_f32 v[192:193], v[8:9], v[192:193]
	v_pk_mul_f32 v[194:195], v[2:3], v[194:195]
	v_pk_mul_f32 v[196:197], v[4:5], v[196:197]
	v_pk_mul_f32 v[190:191], v[190:191], s[30:31]
	v_pk_mul_f32 v[192:193], v[192:193], s[30:31]
	v_pk_mul_f32 v[194:195], v[194:195], s[30:31]
	v_pk_mul_f32 v[196:197], v[196:197], s[30:31]
	v_exp_f32_e32 v190, v190
	v_exp_f32_e32 v191, v191
	v_exp_f32_e32 v192, v192
	v_exp_f32_e32 v193, v193
	v_exp_f32_e32 v194, v194
	v_exp_f32_e32 v195, v195
	v_exp_f32_e32 v196, v196
	v_exp_f32_e32 v197, v197
	v_pk_add_f32 v[190:191], v[190:191], v[188:189]
	v_pk_add_f32 v[192:193], v[192:193], v[188:189]
	v_pk_add_f32 v[194:195], v[194:195], v[188:189]
	v_pk_add_f32 v[196:197], v[196:197], v[188:189]
	v_rcp_f32_e32 v190, v190
	v_rcp_f32_e32 v191, v191
	v_rcp_f32_e32 v192, v192
	v_rcp_f32_e32 v193, v193
	v_rcp_f32_e32 v194, v194
	v_rcp_f32_e32 v195, v195
	v_rcp_f32_e32 v196, v196
	v_rcp_f32_e32 v197, v197
	v_pk_mul_f32 v[6:7], v[6:7], v[190:191]
	v_pk_mul_f32 v[8:9], v[8:9], v[192:193]
	v_pk_mul_f32 v[2:3], v[2:3], v[194:195]
	v_pk_mul_f32 v[4:5], v[4:5], v[196:197]
	v_cvt_pk_bf16_f32 v6, v6, v7
	v_cvt_pk_bf16_f32 v7, v8, v9
	v_cvt_pk_bf16_f32 v8, v2, v3
	v_cvt_pk_bf16_f32 v9, v4, v5
	global_store_dwordx4 v[186:187], v[6:9], off offset:64
